# v48 plus filled trans-hazard nop slots (v46 edit) stacked
# baseline (speedup 1.0000x reference)
; template <int MODE, bool FAST> __device__ __forceinline__ bool attn_unit(LAS unsigned char* lds, const AttU& U, const int wv) {
;     ...
;     if constexpr (FAST) {
;         for (int t2 = U.kt0; t2 < U.kt1; t2 += 2) { ATT_TILE(t2, 4, rk, rr, rv); ATT_TILE(t2 + 1, 4, rk2, rr2, rv2); }
.LBB0_449:
	v_add_f32_e32 v101, v179, v164
	ds_read_b128 v[164:167], v168 offset:18528
	s_or_b64 s[4:5], s[6:7], s[4:5]
	v_add_f32_e32 v100, v178, v185
	s_or_b64 s[4:5], s[4:5], s[8:9]
	s_or_b64 s[4:5], s[4:5], s[10:11]
	v_add_f32_e32 v182, v100, v104
	v_add_f32_e32 v183, v101, v105
	s_xor_b32 s8, s48, 2
	v_exp_f32_e32 v64, v64
	v_exp_f32_e32 v65, v65
	v_mfma_f32_32x32x16_bf16 v[100:115], v[96:99], v[148:151], 0
	v_add_f32_e32 v185, v65, v64
	v_cvt_pk_bf16_f32 v64, v64, v65
	ds_read_b128 v[178:181], v168 offset:9280
	ds_read_b128 v[186:189], v168 offset:9312
	ds_read_b128 v[190:193], v168 offset:13888
	ds_read_b128 v[194:197], v168 offset:13920
	v_exp_f32_e32 v65, v66
	v_exp_f32_e32 v66, v67
	v_add_f32_e32 v67, v65, v185
	v_add_f32_e32 v67, v66, v67
	v_cvt_pk_bf16_f32 v65, v65, v66
	v_mfma_f32_32x32x16_bf16 v[100:115], v[92:95], v[152:155], v[100:115]
	v_exp_f32_e32 v66, v68
	v_exp_f32_e32 v68, v69
	v_add_f32_e32 v67, v66, v67
	v_cvt_pk_bf16_f32 v66, v66, v68
	v_add_f32_e32 v67, v68, v67
	v_mfma_f32_32x32x16_bf16 v[100:115], v[88:91], v[156:159], v[100:115]
	v_exp_f32_e32 v68, v70
	v_exp_f32_e32 v69, v71
	v_add_f32_e32 v70, v68, v67
	v_cvt_pk_bf16_f32 v67, v68, v69
	v_add_f32_e32 v68, v69, v70
	s_waitcnt lgkmcnt(4)
	v_mfma_f32_32x32x16_bf16 v[100:115], v[164:167], v[160:163], v[100:115]
	v_exp_f32_e32 v69, v72
	v_exp_f32_e32 v70, v73
	v_add_f32_e32 v71, v69, v68
	v_cvt_pk_bf16_f32 v68, v69, v70
	v_add_f32_e32 v69, v70, v71
	s_waitcnt lgkmcnt(0)
	v_mfma_f32_32x32x16_bf16 v[16:31], v[178:181], v[80:83], v[16:31]
	v_exp_f32_e32 v70, v74
	v_exp_f32_e32 v71, v75
	v_add_f32_e32 v72, v70, v69
	v_cvt_pk_bf16_f32 v69, v70, v71
	v_add_f32_e32 v70, v71, v72
	v_mfma_f32_32x32x16_bf16 v[16:31], v[186:189], v[84:87], v[16:31]
	v_exp_f32_e32 v71, v76
	v_exp_f32_e32 v72, v77
	v_add_f32_e32 v73, v71, v70
	v_cvt_pk_bf16_f32 v70, v71, v72
	v_add_f32_e32 v71, v72, v73
	v_mfma_f32_32x32x16_bf16 v[0:15], v[190:193], v[80:83], v[0:15]
	v_exp_f32_e32 v72, v78
	v_exp_f32_e32 v73, v79
	v_add_f32_e32 v74, v72, v71
	v_cvt_pk_bf16_f32 v71, v72, v73
	v_add_f32_e32 v198, v73, v74
	v_exp_f32_e32 v88, v100
	v_exp_f32_e32 v89, v101
	v_mfma_f32_32x32x16_bf16 v[0:15], v[194:197], v[84:87], v[0:15]
	v_add_f32_e32 v165, v89, v88
	v_cvt_pk_bf16_f32 v164, v88, v89
	ds_read_b128 v[72:75], v168 offset:23040
	ds_read_b128 v[76:79], v168 offset:23072
	ds_read_b128 v[80:83], v168 offset:23104
	v_cmp_nge_f32_e32 vcc, s62, v198
	ds_read_b128 v[84:87], v168 offset:23136
	v_exp_f32_e32 v166, v102
	v_exp_f32_e32 v167, v103
	s_waitcnt lgkmcnt(1)
	v_mfma_f32_32x32x16_bf16 v[88:103], v[72:75], v[116:119], 0
	ds_read_b128 v[178:181], v168 offset:27648
	ds_read_b128 v[186:189], v168 offset:27680
	ds_read_b128 v[190:193], v168 offset:32256
	ds_read_b128 v[194:197], v168 offset:32288
	v_add_f32_e32 v72, v166, v165
	v_add_f32_e32 v72, v167, v72
	v_cvt_pk_bf16_f32 v165, v166, v167
	v_mfma_f32_32x32x16_bf16 v[88:103], v[76:79], v[120:123], v[88:103]
	v_exp_f32_e32 v73, v104
	v_exp_f32_e32 v74, v105
	v_add_f32_e32 v72, v73, v72
	v_cvt_pk_bf16_f32 v166, v73, v74
	v_add_f32_e32 v72, v74, v72
	v_mfma_f32_32x32x16_bf16 v[88:103], v[80:83], v[124:127], v[88:103]
	v_exp_f32_e32 v73, v106
	v_exp_f32_e32 v74, v107
	v_add_f32_e32 v72, v73, v72
	v_cvt_pk_bf16_f32 v167, v73, v74
	v_add_f32_e32 v72, v74, v72
	s_waitcnt lgkmcnt(4)
	v_mfma_f32_32x32x16_bf16 v[88:103], v[84:87], v[128:131], v[88:103]
	v_exp_f32_e32 v73, v108
	v_exp_f32_e32 v74, v109
	v_add_f32_e32 v75, v73, v72
	v_cvt_pk_bf16_f32 v72, v73, v74
	v_add_f32_e32 v73, v74, v75
	s_waitcnt lgkmcnt(0)
	v_mfma_f32_32x32x16_bf16 v[48:63], v[178:181], v[64:67], v[48:63]
	v_exp_f32_e32 v74, v110
	v_exp_f32_e32 v75, v111
	v_add_f32_e32 v76, v74, v73
	v_cvt_pk_bf16_f32 v73, v74, v75
	v_add_f32_e32 v74, v75, v76
	v_mfma_f32_32x32x16_bf16 v[48:63], v[186:189], v[68:71], v[48:63]
	v_exp_f32_e32 v75, v112
	v_exp_f32_e32 v76, v113
	v_add_f32_e32 v77, v75, v74
	v_cvt_pk_bf16_f32 v74, v75, v76
	v_add_f32_e32 v75, v76, v77
	v_mfma_f32_32x32x16_bf16 v[32:47], v[190:193], v[64:67], v[32:47]
	v_exp_f32_e32 v76, v114
	v_exp_f32_e32 v77, v115
	v_add_f32_e32 v78, v76, v75
	v_cvt_pk_bf16_f32 v75, v76, v77
	v_add_f32_e32 v199, v77, v78
	v_exp_f32_e32 v76, v88
	v_exp_f32_e32 v77, v89
	v_mfma_f32_32x32x16_bf16 v[32:47], v[194:197], v[68:71], v[32:47]
	v_add_f32_e32 v113, v77, v76
	v_cvt_pk_bf16_f32 v112, v76, v77
	ds_read_b128 v[64:67], v168 offset:23040
	ds_read_b128 v[104:107], v168 offset:23072
	ds_read_b128 v[108:111], v168 offset:23104
	s_or_b64 s[6:7], s[4:5], vcc
	v_cmp_nge_f32_e32 vcc, s62, v199
	v_add_f32_e32 v182, v182, v198
	v_add_f32_e32 v183, v183, v199
	ds_read_b128 v[68:71], v168 offset:23136
	v_exp_f32_e32 v114, v90
	v_exp_f32_e32 v115, v91
	s_waitcnt lgkmcnt(1)
; template <int MODE, bool FAST> __device__ __forceinline__ bool attn_unit(LAS unsigned char* lds, const AttU& U, const int wv) {
;     ...
;     if constexpr (FAST) {
;         for (int t2 = U.kt0; t2 < U.kt1; t2 += 2) { ATT_TILE(t2, 4, rk, rr, rv); ATT_TILE(t2 + 1, 4, rk2, rr2, rv2); }
	v_mfma_f32_32x32x16_bf16 v[76:91], v[64:67], v[148:151], 0
	ds_read_b128 v[178:181], v168 offset:27648
	ds_read_b128 v[186:189], v168 offset:27680
	ds_read_b128 v[190:193], v168 offset:32256
	ds_read_b128 v[194:197], v168 offset:32288
	v_add_f32_e32 v64, v114, v113
	v_add_f32_e32 v64, v115, v64
	v_cvt_pk_bf16_f32 v113, v114, v115
	v_mfma_f32_32x32x16_bf16 v[76:91], v[104:107], v[152:155], v[76:91]
	v_exp_f32_e32 v65, v92
	v_exp_f32_e32 v66, v93
	v_add_f32_e32 v64, v65, v64
	v_cvt_pk_bf16_f32 v114, v65, v66
	v_add_f32_e32 v64, v66, v64
	v_mfma_f32_32x32x16_bf16 v[76:91], v[108:111], v[156:159], v[76:91]
	v_exp_f32_e32 v65, v94
	v_exp_f32_e32 v66, v95
	v_add_f32_e32 v64, v65, v64
	v_cvt_pk_bf16_f32 v115, v65, v66
	v_add_f32_e32 v64, v66, v64
	s_waitcnt lgkmcnt(4)
	v_mfma_f32_32x32x16_bf16 v[76:91], v[68:71], v[160:163], v[76:91]
	v_exp_f32_e32 v65, v96
	v_exp_f32_e32 v66, v97
	v_add_f32_e32 v64, v65, v64
	v_cvt_pk_bf16_f32 v92, v65, v66
	v_add_f32_e32 v64, v66, v64
	s_waitcnt lgkmcnt(0)
	v_mfma_f32_32x32x16_bf16 v[16:31], v[178:181], v[164:167], v[16:31]
	v_exp_f32_e32 v65, v98
	v_exp_f32_e32 v66, v99
	v_add_f32_e32 v64, v65, v64
	v_cvt_pk_bf16_f32 v93, v65, v66
	v_add_f32_e32 v64, v66, v64
	v_mfma_f32_32x32x16_bf16 v[16:31], v[186:189], v[72:75], v[16:31]
	v_exp_f32_e32 v65, v100
	v_exp_f32_e32 v66, v101
	v_add_f32_e32 v64, v65, v64
	v_cvt_pk_bf16_f32 v94, v65, v66
	v_add_f32_e32 v64, v66, v64
	v_mfma_f32_32x32x16_bf16 v[0:15], v[190:193], v[164:167], v[0:15]
	v_exp_f32_e32 v65, v102
	v_exp_f32_e32 v66, v103
	v_add_f32_e32 v64, v65, v64
	v_cvt_pk_bf16_f32 v95, v65, v66
	v_add_f32_e32 v198, v66, v64
	s_mulk_i32 s8, 0x4800
	v_exp_f32_e32 v68, v76
	v_exp_f32_e32 v69, v77
	v_mfma_f32_32x32x16_bf16 v[0:15], v[194:197], v[72:75], v[0:15]
	v_add_f32_e32 v97, v69, v68
	v_cvt_pk_bf16_f32 v96, v68, v69
	v_add_u32_e32 v185, s8, v184
	ds_read_b128 v[64:67], v185
	ds_read_b128 v[100:103], v185 offset:32
	ds_read_b128 v[104:107], v185 offset:64
	v_cmp_nge_f32_e64 s[4:5], s62, v198
	ds_read_b128 v[108:111], v185 offset:96
	s_or_b64 s[6:7], s[6:7], vcc
	v_exp_f32_e32 v98, v78
	v_exp_f32_e32 v99, v79
	s_waitcnt lgkmcnt(1)
	v_mfma_f32_32x32x16_bf16 v[64:79], v[64:67], v[116:119], 0
	ds_read_b128 v[164:167], v168 offset:27712
	ds_read_b128 v[178:181], v168 offset:27744
	ds_read_b128 v[186:189], v168 offset:32320
	ds_read_b128 v[190:193], v168 offset:32352
	v_add_f32_e32 v97, v98, v97
	v_add_f32_e32 v168, v99, v97
	v_cvt_pk_bf16_f32 v97, v98, v99
	v_mfma_f32_32x32x16_bf16 v[64:79], v[100:103], v[120:123], v[64:79]
	v_exp_f32_e32 v80, v80
	v_exp_f32_e32 v81, v81
	v_add_f32_e32 v99, v80, v168
	v_cvt_pk_bf16_f32 v98, v80, v81
	v_add_f32_e32 v80, v81, v99
	v_mfma_f32_32x32x16_bf16 v[64:79], v[104:107], v[124:127], v[64:79]
	v_exp_f32_e32 v81, v82
	v_exp_f32_e32 v82, v83
	v_add_f32_e32 v80, v81, v80
	v_cvt_pk_bf16_f32 v99, v81, v82
	v_add_f32_e32 v80, v82, v80
	s_waitcnt lgkmcnt(4)
	v_mfma_f32_32x32x16_bf16 v[64:79], v[108:111], v[128:131], v[64:79]
	v_exp_f32_e32 v81, v84
	v_exp_f32_e32 v82, v85
	v_add_f32_e32 v80, v81, v80
	v_cvt_pk_bf16_f32 v100, v81, v82
	v_add_f32_e32 v80, v82, v80
	s_waitcnt lgkmcnt(0)
	v_mfma_f32_32x32x16_bf16 v[48:63], v[164:167], v[112:115], v[48:63]
	v_exp_f32_e32 v81, v86
	v_exp_f32_e32 v82, v87
	v_add_f32_e32 v80, v81, v80
	v_cvt_pk_bf16_f32 v101, v81, v82
	v_add_f32_e32 v80, v82, v80
	v_mfma_f32_32x32x16_bf16 v[48:63], v[178:181], v[92:95], v[48:63]
	v_exp_f32_e32 v81, v88
	v_exp_f32_e32 v82, v89
	v_add_f32_e32 v80, v81, v80
	v_cvt_pk_bf16_f32 v102, v81, v82
	v_add_f32_e32 v80, v82, v80
	v_mfma_f32_32x32x16_bf16 v[32:47], v[186:189], v[112:115], v[32:47]
	v_exp_f32_e32 v81, v90
	v_exp_f32_e32 v82, v91
	v_add_f32_e32 v80, v81, v80
	v_cvt_pk_bf16_f32 v103, v81, v82
	v_add_f32_e32 v199, v82, v80
	v_mfma_f32_32x32x16_bf16 v[32:47], v[190:193], v[92:95], v[32:47]
	ds_read_b128 v[80:83], v185
	ds_read_b128 v[108:111], v185 offset:32
	ds_read_b128 v[104:107], v185 offset:64
	s_or_b64 s[4:5], s[6:7], s[4:5]
	v_cmp_nge_f32_e32 vcc, s62, v199
	s_or_b64 s[4:5], s[4:5], vcc
	s_cmp_lg_u64 s[4:5], 0
	s_cselect_b64 s[4:5], -1, 0
	s_or_b64 s[42:43], s[42:43], s[4:5]
	v_add_f32_e32 v178, v182, v198
	v_add_f32_e32 v179, v183, v199
	s_add_u32 s46, s46, 0x8000
	s_addc_u32 s47, s47, 0
	s_barrier
	s_waitcnt lgkmcnt(0)
	s_and_b64 vcc, exec, s[44:45]
	s_cbranch_vccnz .LBB0_451
	s_mov_b32 s33, s14
	s_branch .LBB0_437

.LBB0_935:
	s_or_b64 s[6:7], s[8:9], s[6:7]
	v_add_f32_e32 v84, v204, v246
	v_add_f32_e32 v85, v205, v247
	s_or_b64 s[6:7], s[6:7], s[10:11]
	s_or_b64 s[6:7], s[6:7], s[12:13]
	v_add_f32_e32 v178, v84, v210
	v_add_f32_e32 v179, v85, v211
	s_xor_b32 s10, s77, 2
	v_exp_f32_e32 v64, v64
	v_exp_f32_e32 v65, v65
	v_add_u32_e32 v222, s78, v244
	v_add_f32_e32 v84, v65, v64
	v_cvt_pk_bf16_f32 v166, v64, v65
	v_exp_f32_e32 v64, v66
	ds_read_b128 v[204:207], v199 offset:22624
	ds_read_b128 v[208:211], v199 offset:22656
	ds_read_b128 v[218:221], v199 offset:22688
	v_exp_f32_e32 v65, v67
	v_add_f32_e32 v66, v64, v84
	v_mfma_f32_32x32x16_bf16 v[80:95], v[80:83], v[122:125], 0
	v_add_f32_e32 v66, v65, v66
	v_cvt_pk_bf16_f32 v167, v64, v65
	v_mfma_f32_32x32x16_bf16 v[80:95], v[182:185], v[126:129], v[80:95]
	v_exp_f32_e32 v64, v68
	v_exp_f32_e32 v65, v69
	v_add_f32_e32 v66, v64, v66
	v_add_f32_e32 v66, v65, v66
	v_cvt_pk_bf16_f32 v168, v64, v65
	v_mfma_f32_32x32x16_bf16 v[80:95], v[174:177], v[130:133], v[80:95]
	v_exp_f32_e32 v64, v70
	v_exp_f32_e32 v65, v71
	v_add_f32_e32 v66, v64, v66
	v_add_f32_e32 v174, v65, v66
	v_cvt_pk_bf16_f32 v169, v64, v65
	s_waitcnt lgkmcnt(0)
	v_mfma_f32_32x32x16_bf16 v[80:95], v[204:207], v[134:137], v[80:95]
	ds_read_b128 v[64:67], v222 offset:13376
	ds_read_b128 v[68:71], v222 offset:13408
	ds_read_b128 v[180:183], v222 offset:17984
	ds_read_b128 v[222:225], v222 offset:18016
	v_exp_f32_e32 v72, v72
	v_exp_f32_e32 v73, v73
	v_add_f32_e32 v174, v72, v174
	v_add_f32_e32 v175, v73, v174
	v_cvt_pk_bf16_f32 v174, v72, v73
	v_mfma_f32_32x32x16_bf16 v[80:95], v[208:211], v[154:157], v[80:95]
	v_exp_f32_e32 v72, v74
	v_exp_f32_e32 v73, v75
	v_add_f32_e32 v74, v72, v175
	v_add_f32_e32 v74, v73, v74
	v_cvt_pk_bf16_f32 v175, v72, v73
	v_mfma_f32_32x32x16_bf16 v[80:95], v[218:221], v[158:161], v[80:95]
	v_exp_f32_e32 v72, v76
	v_exp_f32_e32 v73, v77
	v_add_f32_e32 v74, v72, v74
	v_add_f32_e32 v74, v73, v74
	v_cvt_pk_bf16_f32 v176, v72, v73
	s_waitcnt lgkmcnt(0)
	v_mfma_f32_32x32x16_bf16 v[16:31], v[64:67], v[162:165], v[16:31]
	v_exp_f32_e32 v64, v78
	v_exp_f32_e32 v65, v79
	v_add_f32_e32 v66, v64, v74
	v_add_f32_e32 v204, v65, v66
	v_cvt_pk_bf16_f32 v177, v64, v65
	v_mfma_f32_32x32x16_bf16 v[0:15], v[180:183], v[162:165], v[0:15]
	ds_read_b128 v[64:67], v199 offset:29184
	ds_read_b128 v[180:183], v199 offset:29216
	ds_read_b128 v[208:211], v199 offset:29248
	v_cmp_nge_f32_e32 vcc, s48, v204
	v_mfma_f32_32x32x16_bf16 v[16:31], v[68:71], v[170:173], v[16:31]
	v_mfma_f32_32x32x16_bf16 v[0:15], v[222:225], v[170:173], v[0:15]
	v_mad_u32_u24 v68, v187, s69, v186
	v_add_u32_e32 v206, s76, v68
	v_exp_f32_e32 v68, v80
	v_exp_f32_e32 v69, v81
	v_exp_f32_e32 v80, v82
	v_add_f32_e32 v70, v69, v68
	v_cvt_pk_bf16_f32 v162, v68, v69
	ds_read_b128 v[170:173], v199 offset:29280
	ds_read_b128 v[218:221], v199 offset:29312
	ds_read_b128 v[222:225], v199 offset:29344
	v_exp_f32_e32 v81, v83
	v_add_f32_e32 v82, v80, v70
	s_waitcnt lgkmcnt(3)
	v_mfma_f32_32x32x16_bf16 v[64:79], v[64:67], v[98:101], 0
	v_add_f32_e32 v82, v81, v82
	v_cvt_pk_bf16_f32 v163, v80, v81
	v_mfma_f32_32x32x16_bf16 v[64:79], v[180:183], v[102:105], v[64:79]
	v_exp_f32_e32 v80, v84
	v_exp_f32_e32 v81, v85
	v_add_f32_e32 v82, v80, v82
	v_add_f32_e32 v82, v81, v82
	v_cvt_pk_bf16_f32 v164, v80, v81
	v_mfma_f32_32x32x16_bf16 v[64:79], v[208:211], v[106:109], v[64:79]
	v_exp_f32_e32 v80, v86
	v_exp_f32_e32 v81, v87
	v_add_f32_e32 v82, v80, v82
	v_add_f32_e32 v184, v81, v82
	v_cvt_pk_bf16_f32 v165, v80, v81
	s_waitcnt lgkmcnt(0)
	v_mfma_f32_32x32x16_bf16 v[64:79], v[170:173], v[110:113], v[64:79]
	ds_read_b128 v[80:83], v206 offset:35840
	ds_read_b128 v[84:87], v206 offset:35872
	ds_read_b128 v[180:183], v206 offset:40448
	ds_read_b128 v[208:211], v206 offset:40480
	v_exp_f32_e32 v88, v88
	v_exp_f32_e32 v89, v89
	v_add_f32_e32 v170, v88, v184
	v_add_f32_e32 v171, v89, v170
	v_cvt_pk_bf16_f32 v170, v88, v89
	v_mfma_f32_32x32x16_bf16 v[64:79], v[218:221], v[114:117], v[64:79]
	v_exp_f32_e32 v88, v90
	v_exp_f32_e32 v89, v91
	v_add_f32_e32 v90, v88, v171
	v_add_f32_e32 v90, v89, v90
	v_cvt_pk_bf16_f32 v171, v88, v89
	v_mfma_f32_32x32x16_bf16 v[64:79], v[222:225], v[118:121], v[64:79]
	v_exp_f32_e32 v88, v92
	v_exp_f32_e32 v89, v93
	v_add_f32_e32 v90, v88, v90
	v_add_f32_e32 v90, v89, v90
	v_cvt_pk_bf16_f32 v172, v88, v89
	s_waitcnt lgkmcnt(0)
	v_mfma_f32_32x32x16_bf16 v[48:63], v[80:83], v[166:169], v[48:63]
	v_exp_f32_e32 v80, v94
	v_exp_f32_e32 v81, v95
	v_add_f32_e32 v82, v80, v90
	v_add_f32_e32 v205, v81, v82
	v_cvt_pk_bf16_f32 v173, v80, v81
	v_mfma_f32_32x32x16_bf16 v[32:47], v[180:183], v[166:169], v[32:47]
	ds_read_b128 v[80:83], v199 offset:29184
	ds_read_b128 v[166:169], v199 offset:29216
	ds_read_b128 v[182:185], v199 offset:29248
	s_or_b64 s[8:9], s[6:7], vcc
	v_cmp_nge_f32_e32 vcc, s48, v205
	v_add_f32_e32 v204, v178, v204
	v_add_f32_e32 v205, v179, v205
	v_mfma_f32_32x32x16_bf16 v[48:63], v[84:87], v[174:177], v[48:63]
	v_exp_f32_e32 v64, v64
	v_exp_f32_e32 v65, v65
	s_nop 0
	v_add_f32_e32 v84, v65, v64
	v_cvt_pk_bf16_f32 v178, v64, v65
	v_exp_f32_e32 v64, v66
	v_exp_f32_e32 v65, v67
	v_add_f32_e32 v66, v64, v84
	v_mfma_f32_32x32x16_bf16 v[32:47], v[208:211], v[174:177], v[32:47]
	ds_read_b128 v[174:177], v199 offset:29280
	ds_read_b128 v[208:211], v199 offset:29312
	ds_read_b128 v[218:221], v199 offset:29344
	s_waitcnt lgkmcnt(3)
; template <int MODE, bool FAST> __device__ __forceinline__ bool attn_unit(LAS unsigned char* lds, const AttU& U, const int wv) {
;     ...
;     if constexpr (FAST) {
;         for (int t2 = U.kt0; t2 < U.kt1; t2 += 2) { ATT_TILE(t2, 4, rk, rr, rv); ATT_TILE(t2 + 1, 4, rk2, rr2, rv2); }
	v_mfma_f32_32x32x16_bf16 v[80:95], v[80:83], v[122:125], 0
	v_add_f32_e32 v66, v65, v66
	v_cvt_pk_bf16_f32 v179, v64, v65
	v_mfma_f32_32x32x16_bf16 v[80:95], v[166:169], v[126:129], v[80:95]
	v_exp_f32_e32 v64, v68
	v_exp_f32_e32 v65, v69
	v_add_f32_e32 v66, v64, v66
	v_add_f32_e32 v66, v65, v66
	v_cvt_pk_bf16_f32 v180, v64, v65
	v_mfma_f32_32x32x16_bf16 v[80:95], v[182:185], v[130:133], v[80:95]
	v_exp_f32_e32 v64, v70
	v_exp_f32_e32 v65, v71
	v_add_f32_e32 v66, v64, v66
	v_add_f32_e32 v182, v65, v66
	v_cvt_pk_bf16_f32 v181, v64, v65
	s_waitcnt lgkmcnt(0)
	v_mfma_f32_32x32x16_bf16 v[80:95], v[174:177], v[134:137], v[80:95]
	ds_read_b128 v[64:67], v206 offset:35840
	ds_read_b128 v[68:71], v206 offset:35872
	ds_read_b128 v[166:169], v206 offset:40448
	ds_read_b128 v[222:225], v206 offset:40480
	v_exp_f32_e32 v72, v72
	v_exp_f32_e32 v73, v73
	v_add_f32_e32 v174, v72, v182
	v_add_f32_e32 v174, v73, v174
	v_cvt_pk_bf16_f32 v182, v72, v73
	v_mfma_f32_32x32x16_bf16 v[80:95], v[208:211], v[154:157], v[80:95]
	v_exp_f32_e32 v72, v74
	v_exp_f32_e32 v73, v75
	v_add_f32_e32 v74, v72, v174
	v_add_f32_e32 v74, v73, v74
	v_cvt_pk_bf16_f32 v183, v72, v73
	v_mfma_f32_32x32x16_bf16 v[80:95], v[218:221], v[158:161], v[80:95]
	v_exp_f32_e32 v72, v76
	v_exp_f32_e32 v73, v77
	v_add_f32_e32 v74, v72, v74
	v_add_f32_e32 v74, v73, v74
	v_cvt_pk_bf16_f32 v184, v72, v73
	s_waitcnt lgkmcnt(0)
	v_mfma_f32_32x32x16_bf16 v[16:31], v[64:67], v[162:165], v[16:31]
	v_exp_f32_e32 v64, v78
	v_exp_f32_e32 v65, v79
	v_add_f32_e32 v66, v64, v74
	v_add_f32_e32 v226, v65, v66
	v_cvt_pk_bf16_f32 v185, v64, v65
	v_mfma_f32_32x32x16_bf16 v[0:15], v[166:169], v[162:165], v[0:15]
	s_mulk_i32 s10, 0x5800
	v_add_u32_e32 v199, s10, v242
	ds_read_b128 v[64:67], v199
	ds_read_b128 v[164:167], v199 offset:32
	ds_read_b128 v[174:177], v199 offset:64
	v_cmp_nge_f32_e64 s[6:7], s48, v226
	v_mfma_f32_32x32x16_bf16 v[16:31], v[68:71], v[170:173], v[16:31]
	v_exp_f32_e32 v68, v80
	v_exp_f32_e32 v69, v81
	v_exp_f32_e32 v80, v82
	v_add_f32_e32 v70, v69, v68
	v_cvt_pk_bf16_f32 v162, v68, v69
	v_exp_f32_e32 v81, v83
	v_add_f32_e32 v82, v80, v70
	v_mfma_f32_32x32x16_bf16 v[0:15], v[222:225], v[170:173], v[0:15]
	s_or_b64 s[8:9], s[8:9], vcc
	ds_read_b128 v[168:171], v199 offset:96
	ds_read_b128 v[208:211], v199 offset:128
	ds_read_b128 v[218:221], v199 offset:160
	s_waitcnt lgkmcnt(3)
	v_mfma_f32_32x32x16_bf16 v[64:79], v[64:67], v[98:101], 0
	v_add_f32_e32 v82, v81, v82
	v_cvt_pk_bf16_f32 v163, v80, v81
	v_mfma_f32_32x32x16_bf16 v[64:79], v[164:167], v[102:105], v[64:79]
	v_exp_f32_e32 v80, v84
	v_exp_f32_e32 v81, v85
	v_add_f32_e32 v82, v80, v82
	v_add_f32_e32 v82, v81, v82
	v_cvt_pk_bf16_f32 v164, v80, v81
	v_mfma_f32_32x32x16_bf16 v[64:79], v[174:177], v[106:109], v[64:79]
	v_exp_f32_e32 v80, v86
	v_exp_f32_e32 v81, v87
	v_add_f32_e32 v82, v80, v82
	v_add_f32_e32 v166, v81, v82
	v_cvt_pk_bf16_f32 v165, v80, v81
	s_waitcnt lgkmcnt(0)
	v_mfma_f32_32x32x16_bf16 v[64:79], v[168:171], v[110:113], v[64:79]
	ds_read_b128 v[80:83], v206 offset:35904
	ds_read_b128 v[84:87], v206 offset:35936
	ds_read_b128 v[222:225], v206 offset:40512
	ds_read_b128 v[246:249], v206 offset:40544
	v_exp_f32_e32 v88, v88
	v_exp_f32_e32 v89, v89
	v_add_f32_e32 v166, v88, v166
	v_add_f32_e32 v167, v89, v166
	v_cvt_pk_bf16_f32 v166, v88, v89
	v_mfma_f32_32x32x16_bf16 v[64:79], v[208:211], v[114:117], v[64:79]
	v_exp_f32_e32 v88, v90
	v_exp_f32_e32 v89, v91
	v_add_f32_e32 v90, v88, v167
	v_add_f32_e32 v90, v89, v90
	v_cvt_pk_bf16_f32 v167, v88, v89
	v_mfma_f32_32x32x16_bf16 v[64:79], v[218:221], v[118:121], v[64:79]
	v_exp_f32_e32 v88, v92
	v_exp_f32_e32 v89, v93
	v_add_f32_e32 v90, v88, v90
	v_add_f32_e32 v90, v89, v90
	v_cvt_pk_bf16_f32 v168, v88, v89
	s_waitcnt lgkmcnt(0)
	v_mfma_f32_32x32x16_bf16 v[48:63], v[80:83], v[178:181], v[48:63]
	v_exp_f32_e32 v80, v94
	v_exp_f32_e32 v81, v95
	v_add_f32_e32 v82, v80, v90
	v_add_f32_e32 v227, v81, v82
	v_cvt_pk_bf16_f32 v169, v80, v81
	v_mfma_f32_32x32x16_bf16 v[32:47], v[222:225], v[178:181], v[32:47]
	ds_read_b128 v[80:83], v199
	ds_read_b128 v[174:177], v199 offset:32
	ds_read_b128 v[170:173], v199 offset:64
	s_or_b64 s[6:7], s[8:9], s[6:7]
	v_cmp_nge_f32_e32 vcc, s48, v227
	s_or_b64 s[6:7], s[6:7], vcc
	s_cmp_lg_u64 s[6:7], 0
	s_cselect_b64 s[6:7], -1, 0
	s_or_b64 s[42:43], s[42:43], s[6:7]
	v_mfma_f32_32x32x16_bf16 v[48:63], v[84:87], v[182:185], v[48:63]
	v_add_f32_e64 v204, v204, v226
	v_add_f32_e64 v205, v205, v227
	s_add_u32 s40, s40, 0x40000
	s_mov_b64 s[6:7], 0x2000
	s_addc_u32 s41, s41, 0
	v_lshl_add_u64 v[202:203], v[202:203], 0, s[6:7]
	s_barrier
	s_waitcnt lgkmcnt(0)
	v_mfma_f32_32x32x16_bf16 v[32:47], v[246:249], v[182:185], v[32:47]
	s_and_b64 vcc, exec, s[44:45]
	s_cbranch_vccnz .LBB0_937
	s_mov_b32 s61, s30
	s_branch .LBB0_923
